# attention V tile in LDS re-pitched to 144 B rows with permuted 8-byte key groups so PV fragments are single ds_read_b128 (was ds_read2_b64 at half LDS rate)
# speedup vs baseline: 1.0003x; 1.0003x over previous
.LBB0_381:
	s_and_b64 s[0:1], s[76:77], exec
	s_cselect_b32 s6, s2, s90
	v_mov_b32_e32 v56, v206
	s_lshl_b32 s68, s6, 8
	v_ashrrev_i32_e32 v60, 6, v56
	v_and_b32_e32 v57, 31, v56
	v_lshl_add_u32 v59, v60, 5, s68
	v_or_b32_e32 v198, v59, v57
	v_ashrrev_i32_e32 v199, 31, v198
	v_lshl_add_u64 v[196:197], s[64:65], 0, v[198:199]
	v_mov_b64_e32 v[2:3], s[16:17]
	v_mad_u64_u32 v[2:3], s[0:1], v196, s89, v[2:3]
	v_bfe_u32 v58, v56, 5, 1
	v_mad_i32_i24 v3, v197, s89, v3
	s_lshl_b32 s0, s82, 1
	s_mov_b32 s1, s55
	v_lshl_add_u64 v[4:5], v[2:3], 0, s[0:1]
	v_lshlrev_b32_e32 v0, 4, v58
	v_lshl_add_u64 v[4:5], v[4:5], 0, v[0:1]
	global_load_dwordx4 v[48:51], v[4:5], off
	global_load_dwordx4 v[44:47], v[4:5], off offset:32
	global_load_dwordx4 v[36:39], v[4:5], off offset:64
	global_load_dwordx4 v[40:43], v[4:5], off offset:96
	v_lshl_add_u64 v[2:3], v[2:3], 0, s[54:55]
	v_lshl_add_u64 v[2:3], v[2:3], 0, v[0:1]
	s_movk_i32 s0, 0x1000
	v_add_co_u32_e32 v32, vcc, s0, v2
	v_mov_b64_e32 v[14:15], s[12:13]
	s_nop 0
	v_addc_co_u32_e32 v33, vcc, 0, v3, vcc
	global_load_dwordx4 v[52:55], v[4:5], off offset:128
	global_load_dwordx4 v[62:65], v[4:5], off offset:160
	global_load_dwordx4 v[66:69], v[4:5], off offset:192
	global_load_dwordx4 v[70:73], v[4:5], off offset:224
	s_nop 0
	global_load_dwordx4 v[2:5], v[32:33], off
	global_load_dwordx4 v[10:13], v[32:33], off offset:32
	global_load_dwordx4 v[6:9], v[32:33], off offset:64
	s_nop 0
	global_load_dwordx4 v[32:35], v[32:33], off offset:96
	s_nop 0
	global_load_dwordx2 v[14:15], v[14:15], off sc1
	s_waitcnt vmcnt(0) lgkmcnt(0)
	v_and_b32_e32 v75, 0xffff0000, v49
	v_and_b32_e32 v79, 0xffff0000, v48
	v_and_b32_e32 v78, 0xffff0000, v50
	v_lshlrev_b32_e32 v74, 16, v49
	v_lshlrev_b32_e32 v77, 16, v48
	v_lshlrev_b32_e32 v76, 16, v50
	v_lshlrev_b32_e32 v90, 16, v36
	v_and_b32_e32 v91, 0xffff0000, v36
	v_lshlrev_b32_e32 v92, 16, v37
	v_and_b32_e32 v93, 0xffff0000, v37
	v_lshlrev_b32_e32 v94, 16, v38
	v_and_b32_e32 v96, 0xffff0000, v38
	v_pk_mov_b32 v[36:37], v[38:39], v[42:43] op_sel:[1,0]
	v_lshlrev_b32_e32 v50, 16, v39
	v_mul_f32_e32 v0, v75, v75
	v_pk_mul_f32 v[38:39], v[78:79], v[78:79]
	v_lshlrev_b32_e32 v61, 16, v41
	v_and_b32_e32 v122, 0xffff0000, v41
	v_lshlrev_b32_e32 v41, 16, v43
	v_lshlrev_b32_e32 v95, 16, v40
	v_and_b32_e32 v97, 0xffff0000, v40
	v_mul_f32_e32 v40, v91, v91
	v_mul_f32_e32 v48, v93, v93
	v_pk_fma_f32 v[98:99], v[74:75], v[74:75], v[0:1] op_sel_hi:[1,1,0]
	v_pk_fma_f32 v[38:39], v[76:77], v[76:77], v[38:39]
	v_mul_f32_e32 v102, v61, v61
	v_mul_f32_e32 v103, v122, v122
	v_pk_fma_f32 v[100:101], v[90:91], v[90:91], v[40:41] op_sel_hi:[1,1,0]
	v_pk_fma_f32 v[48:49], v[92:93], v[92:93], v[48:49] op_sel_hi:[1,1,0]
	v_pk_add_f32 v[98:99], v[38:39], v[98:99] op_sel:[1,0] op_sel_hi:[0,1]
	v_and_b32_e32 v85, 0xffff0000, v45
	v_and_b32_e32 v84, 0xffff0000, v44
	v_lshlrev_b32_e32 v87, 16, v47
	v_lshlrev_b32_e32 v86, 16, v46
	v_and_b32_e32 v89, 0xffff0000, v47
	v_and_b32_e32 v88, 0xffff0000, v46
	v_pk_mul_f32 v[46:47], v[96:97], v[96:97]
	v_mov_b32_e32 v101, v102
	v_mov_b32_e32 v49, v103
	v_pk_add_f32 v[38:39], v[38:39], v[98:99]
	v_and_b32_e32 v99, 0xffff0000, v37
	v_and_b32_e32 v98, 0xffff0000, v36
	v_lshlrev_b32_e32 v80, 16, v51
	v_and_b32_e32 v81, 0xffff0000, v51
	v_lshlrev_b32_e32 v83, 16, v45
	v_lshlrev_b32_e32 v82, 16, v44
	v_and_b32_e32 v123, 0xffff0000, v43
	v_lshlrev_b32_e32 v51, 16, v42
	v_pk_mul_f32 v[42:43], v[84:85], v[84:85]
	v_pk_fma_f32 v[46:47], v[94:95], v[94:95], v[46:47]
	v_pk_add_f32 v[48:49], v[100:101], v[48:49]
	v_pk_mul_f32 v[36:37], v[98:99], v[98:99]
	v_pk_mul_f32 v[44:45], v[88:89], v[88:89]
	v_pk_fma_f32 v[42:43], v[82:83], v[82:83], v[42:43]
	v_pk_add_f32 v[46:47], v[46:47], v[48:49]
	v_pk_fma_f32 v[36:37], v[50:51], v[50:51], v[36:37]
	v_mul_f32_e32 v0, v81, v81
	v_pk_fma_f32 v[44:45], v[86:87], v[86:87], v[44:45]
	v_pk_add_f32 v[42:43], v[42:43], v[42:43] op_sel:[0,1] op_sel_hi:[1,0]
	v_pk_add_f32 v[36:37], v[36:37], v[46:47]
	v_pk_fma_f32 v[46:47], v[80:81], v[80:81], v[0:1] op_sel_hi:[1,1,0]
	v_pk_add_f32 v[42:43], v[44:45], v[42:43]
	v_mov_b32_e32 v40, v46
	v_mov_b32_e32 v48, v38
	v_mov_b32_e32 v49, v41
	v_mul_f32_e32 v104, v123, v123
	v_pk_add_f32 v[38:39], v[46:47], v[38:39]
	v_pk_mul_f32 v[46:47], v[40:41], v[48:49]
	v_pk_add_f32 v[42:43], v[44:45], v[42:43] op_sel:[1,0] op_sel_hi:[0,1]
	v_mov_b32_e32 v39, v47
	v_mov_b32_e32 v43, v104
	v_pk_add_f32 v[38:39], v[38:39], v[42:43]
	v_and_b32_e32 v105, 0xffff0000, v53
	v_and_b32_e32 v104, 0xffff0000, v52
	v_readfirstlane_b32 s0, v14
	v_pk_add_f32 v[100:101], v[38:39], v[36:37]
	v_lshlrev_b32_e32 v103, 16, v53
	v_lshlrev_b32_e32 v102, 16, v52
	v_pk_mul_f32 v[36:37], v[104:105], v[104:105]
	v_readfirstlane_b32 s1, v15
	s_add_u32 s0, s0, s18
	v_pk_fma_f32 v[36:37], v[102:103], v[102:103], v[36:37]
	s_addc_u32 s1, s1, s19
	v_lshlrev_b32_e32 v0, 5, v58
	v_pk_add_f32 v[38:39], v[36:37], v[36:37] op_sel:[0,1] op_sel_hi:[1,0]
	v_mov_b64_e32 v[14:15], s[14:15]
	v_lshl_add_u64 v[36:37], s[0:1], 0, v[0:1]
	global_load_dwordx2 v[14:15], v[14:15], off sc1
	v_lshlrev_b32_e32 v107, 16, v55
	global_load_dwordx2 v[108:109], v[36:37], off
	global_load_dwordx2 v[164:165], v[36:37], off offset:8
	global_load_dwordx2 v[166:167], v[36:37], off offset:16
	global_load_dwordx2 v[168:169], v[36:37], off offset:24
	global_load_dwordx2 v[170:171], v[36:37], off offset:64
	global_load_dwordx2 v[172:173], v[36:37], off offset:72
	global_load_dwordx2 v[174:175], v[36:37], off offset:80
	global_load_dwordx2 v[176:177], v[36:37], off offset:88
	global_load_dwordx2 v[178:179], v[36:37], off offset:128
	global_load_dwordx2 v[180:181], v[36:37], off offset:136
	global_load_dwordx2 v[182:183], v[36:37], off offset:144
	global_load_dwordx2 v[184:185], v[36:37], off offset:152
	global_load_dwordx2 v[186:187], v[36:37], off offset:192
	global_load_dwordx2 v[188:189], v[36:37], off offset:200
	global_load_dwordx2 v[190:191], v[36:37], off offset:208
	global_load_dwordx2 v[192:193], v[36:37], off offset:216
	global_load_dwordx2 v[194:195], v[36:37], off offset:256
	global_load_dwordx2 v[208:209], v[36:37], off offset:264
	global_load_dwordx2 v[210:211], v[36:37], off offset:272
	global_load_dwordx2 v[240:241], v[36:37], off offset:280
	global_load_dwordx2 v[242:243], v[36:37], off offset:320
	v_lshlrev_b32_e32 v106, 16, v54
	v_and_b32_e32 v55, 0xffff0000, v55
	v_and_b32_e32 v54, 0xffff0000, v54
	v_pk_mul_f32 v[42:43], v[54:55], v[54:55]
	v_lshlrev_b32_e32 v113, 16, v63
	v_pk_fma_f32 v[42:43], v[106:107], v[106:107], v[42:43]
	v_lshlrev_b32_e32 v112, 16, v62
	v_pk_add_f32 v[38:39], v[42:43], v[38:39]
	v_and_b32_e32 v63, 0xffff0000, v63
	v_and_b32_e32 v62, 0xffff0000, v62
	v_lshlrev_b32_e32 v115, 16, v65
	v_lshlrev_b32_e32 v114, 16, v64
	v_and_b32_e32 v65, 0xffff0000, v65
	v_and_b32_e32 v64, 0xffff0000, v64
	v_and_b32_e32 v121, 0xffff0000, v66
	v_pk_add_f32 v[110:111], v[42:43], v[38:39] op_sel:[1,0] op_sel_hi:[0,1]
	v_pk_mul_f32 v[38:39], v[62:63], v[62:63]
	v_pk_mul_f32 v[42:43], v[64:65], v[64:65]
	v_lshlrev_b32_e32 v120, 16, v66
	v_and_b32_e32 v53, 0xffff0000, v67
	v_mul_f32_e32 v40, v121, v121
	v_pk_fma_f32 v[38:39], v[112:113], v[112:113], v[38:39]
	v_pk_fma_f32 v[116:117], v[114:115], v[114:115], v[42:43]
	v_lshlrev_b32_e32 v52, 16, v67
	v_lshlrev_b32_e32 v124, 16, v71
	v_and_b32_e32 v125, 0xffff0000, v71
	v_pk_fma_f32 v[42:43], v[120:121], v[120:121], v[40:41] op_sel_hi:[1,1,0]
	v_mul_f32_e32 v40, v53, v53
	v_pk_add_f32 v[38:39], v[38:39], v[38:39] op_sel:[0,1] op_sel_hi:[1,0]
	v_mul_f32_e32 v46, v124, v124
	v_mul_f32_e32 v71, v125, v125
	v_and_b32_e32 v45, 0xffff0000, v70
	v_and_b32_e32 v44, 0xffff0000, v68
	v_pk_fma_f32 v[66:67], v[52:53], v[52:53], v[40:41] op_sel_hi:[1,1,0]
	v_pk_add_f32 v[118:119], v[116:117], v[38:39]
	v_lshlrev_b32_e32 v49, 16, v70
	v_lshlrev_b32_e32 v48, 16, v68
	v_pk_mul_f32 v[38:39], v[44:45], v[44:45]
	v_mov_b32_e32 v43, v46
	v_mov_b32_e32 v67, v71
	v_pk_fma_f32 v[38:39], v[48:49], v[48:49], v[38:39]
	v_pk_add_f32 v[42:43], v[42:43], v[66:67]
	v_lshlrev_b32_e32 v47, 16, v73
	v_pk_add_f32 v[66:67], v[38:39], v[42:43]
	v_pk_mov_b32 v[38:39], v[68:69], v[72:73] op_sel:[1,0]
	v_lshlrev_b32_e32 v43, 16, v72
	v_and_b32_e32 v39, 0xffff0000, v39
	v_and_b32_e32 v38, 0xffff0000, v38
	v_lshlrev_b32_e32 v42, 16, v69
	v_pk_mul_f32 v[68:69], v[38:39], v[38:39]
	v_mov_b32_e32 v70, v110
	v_pk_fma_f32 v[68:69], v[42:43], v[42:43], v[68:69]
	v_mov_b32_e32 v71, v47
	v_pk_add_f32 v[66:67], v[68:69], v[66:67]
	v_pk_add_f32 v[68:69], v[100:101], v[100:101] op_sel:[0,1] op_sel_hi:[1,0]
	v_and_b32_e32 v126, 0xffff0000, v73
	v_mov_b32_e32 v46, v68
	v_pk_add_f32 v[68:69], v[68:69], v[110:111]
	v_pk_mul_f32 v[70:71], v[46:47], v[70:71]
	v_mul_f32_e32 v127, v126, v126
	v_mov_b32_e32 v69, v71
	v_pk_add_f32 v[70:71], v[116:117], v[118:119] op_sel:[1,0] op_sel_hi:[0,1]
	v_mov_b32_e32 v71, v127
	v_pk_add_f32 v[68:69], v[68:69], v[70:71]
	s_waitcnt vmcnt(0) lgkmcnt(0)
	v_readfirstlane_b32 s0, v14
	v_pk_add_f32 v[66:67], v[68:69], v[66:67]
	v_readfirstlane_b32 s1, v15
	v_pk_add_f32 v[66:67], v[66:67], v[66:67] op_sel:[0,1] op_sel_hi:[1,0]
	s_add_u32 s0, s0, s40
	v_mov_b32_e32 v40, v66
	s_nop 1
	v_permlane32_swap_b32_e32 v66, v40
	v_add_f32_e32 v40, v66, v40
	v_fmamk_f32 v40, v40, 0x3c000000, v207
	v_mul_f32_e32 v46, 0x4b800000, v40
	v_cmp_gt_f32_e32 vcc, s87, v40
	s_addc_u32 s1, s1, s41
	v_lshlrev_b32_e32 v15, 16, v13
	v_cndmask_b32_e32 v40, v40, v46, vcc
	v_rsq_f32_e32 v40, v40
	v_lshlrev_b32_e32 v14, 16, v35
	v_mul_f32_e32 v46, 0x45800000, v40
	v_cndmask_b32_e32 v40, v40, v46, vcc
	v_mul_f32_e32 v68, 0x3dd53b94, v40
	v_mul_f32_e32 v40, v68, v77
	v_mul_f32_e32 v46, v68, v79
	v_mul_f32_e32 v40, v108, v40
	v_mul_f32_e32 v46, v109, v46
	v_cvt_pk_bf16_f32 v128, v40, v46
	v_mov_b32_e32 v66, v164
	v_mov_b32_e32 v67, v165
	v_mul_f32_e32 v40, v68, v74
	v_mul_f32_e32 v46, v68, v75
	v_mul_f32_e32 v44, v68, v44
	v_mul_f32_e32 v42, v68, v42
	v_mul_f32_e32 v38, v68, v38
	v_mul_f32_e32 v39, v68, v39
	v_mul_f32_e32 v40, v66, v40
	v_mul_f32_e32 v46, v67, v46
	v_cvt_pk_bf16_f32 v129, v40, v46
	v_mov_b32_e32 v66, v166
	v_mov_b32_e32 v67, v167
	v_mul_f32_e32 v40, v68, v76
	v_mul_f32_e32 v46, v68, v78
	v_mul_f32_e32 v40, v40, v66
	v_mul_f32_e32 v46, v46, v67
	v_cvt_pk_bf16_f32 v130, v40, v46
	v_mov_b32_e32 v66, v168
	v_mov_b32_e32 v67, v169
	v_mul_f32_e32 v40, v68, v80
	v_mul_f32_e32 v46, v68, v81
	v_mul_f32_e32 v40, v40, v66
	v_mul_f32_e32 v46, v46, v67
	v_cvt_pk_bf16_f32 v131, v40, v46
	v_mov_b32_e32 v66, v170
	v_mov_b32_e32 v67, v171
	v_mul_f32_e32 v40, v68, v82
	v_mul_f32_e32 v46, v68, v84
	v_lshlrev_b32_e32 v82, 16, v8
	v_and_b32_e32 v84, 0xffff0000, v8
	v_mov_b32_e32 v162, v84
	v_mov_b32_e32 v160, v82
	v_mul_f32_e32 v40, v40, v66
	v_mul_f32_e32 v46, v46, v67
	v_cvt_pk_bf16_f32 v132, v40, v46
	v_mov_b32_e32 v66, v172
	v_mov_b32_e32 v67, v173
	v_mul_f32_e32 v40, v68, v83
	v_mul_f32_e32 v46, v68, v85
	v_lshlrev_b32_e32 v83, 16, v4
	v_and_b32_e32 v85, 0xffff0000, v4
	v_mov_b32_e32 v111, v83
	v_mul_f32_e32 v40, v40, v66
	v_mul_f32_e32 v46, v46, v67
	v_cvt_pk_bf16_f32 v133, v40, v46
	v_mov_b32_e32 v66, v174
	v_mov_b32_e32 v67, v175
	v_mul_f32_e32 v40, v68, v86
	v_mul_f32_e32 v46, v68, v88
	v_lshlrev_b32_e32 v86, 16, v7
	v_and_b32_e32 v88, 0xffff0000, v7
	v_mul_f32_e32 v40, v40, v66
	v_mul_f32_e32 v46, v46, v67
	v_cvt_pk_bf16_f32 v134, v40, v46
	v_mov_b32_e32 v66, v176
	v_mov_b32_e32 v67, v177
	v_mul_f32_e32 v40, v68, v87
	v_mul_f32_e32 v46, v68, v89
	v_lshlrev_b32_e32 v87, 16, v3
	v_and_b32_e32 v89, 0xffff0000, v3
	v_mov_b32_e32 v119, v87
	v_mul_f32_e32 v40, v40, v66
	v_mul_f32_e32 v46, v46, v67
	v_cvt_pk_bf16_f32 v135, v40, v46
	v_mov_b32_e32 v66, v178
	v_mov_b32_e32 v67, v179
	v_mul_f32_e32 v40, v68, v90
	v_mul_f32_e32 v46, v68, v91
	v_lshlrev_b32_e32 v91, 16, v2
	v_lshlrev_b32_e32 v90, 16, v6
	v_mov_b32_e32 v116, v90
	v_mov_b32_e32 v118, v91
	v_mul_f32_e32 v40, v40, v66
	v_mul_f32_e32 v46, v46, v67
	v_cvt_pk_bf16_f32 v136, v40, v46
	v_mov_b32_e32 v66, v180
	v_mov_b32_e32 v67, v181
	v_mul_f32_e32 v40, v68, v92
	v_mul_f32_e32 v46, v68, v93
	v_and_b32_e32 v93, 0xffff0000, v2
	v_mul_f32_e32 v2, v68, v126
	v_and_b32_e32 v92, 0xffff0000, v6
	v_mov_b32_e32 v117, v92
	v_mul_f32_e32 v40, v40, v66
	v_mul_f32_e32 v46, v46, v67
	v_cvt_pk_bf16_f32 v137, v40, v46
	v_mov_b32_e32 v66, v182
	v_mov_b32_e32 v67, v183
	v_mul_f32_e32 v40, v68, v94
	v_mul_f32_e32 v46, v68, v96
	v_mul_f32_e32 v40, v40, v66
	v_mul_f32_e32 v46, v46, v67
	v_cvt_pk_bf16_f32 v138, v40, v46
	v_mov_b32_e32 v66, v184
	v_mov_b32_e32 v67, v185
	v_mul_f32_e32 v40, v68, v50
	v_mul_f32_e32 v46, v68, v98
	v_mov_b32_e32 v98, v15
	v_mul_f32_e32 v40, v40, v66
	v_mul_f32_e32 v46, v46, v67
	v_cvt_pk_bf16_f32 v139, v40, v46
	v_mov_b32_e32 v66, v186
	v_mov_b32_e32 v67, v187
	v_mul_f32_e32 v40, v68, v95
	v_mul_f32_e32 v46, v68, v97
	v_pk_mul_f32 v[94:95], v[14:15], v[14:15]
	v_mul_f32_e32 v40, v40, v66
	v_mul_f32_e32 v46, v46, v67
	v_cvt_pk_bf16_f32 v140, v40, v46
	v_mov_b32_e32 v66, v188
	v_mov_b32_e32 v67, v189
	v_mul_f32_e32 v40, v68, v61
	v_mul_f32_e32 v46, v68, v122
	v_mul_f32_e32 v122, v92, v92
	v_pk_fma_f32 v[116:117], v[116:117], v[116:117], v[122:123] op_sel_hi:[1,1,0]
	v_mul_f32_e32 v40, v40, v66
	v_mul_f32_e32 v46, v46, v67
	v_cvt_pk_bf16_f32 v141, v40, v46
	v_mov_b32_e32 v66, v190
	v_mov_b32_e32 v67, v191
	v_mul_f32_e32 v40, v68, v51
	v_mul_f32_e32 v46, v68, v99
	v_mul_f32_e32 v40, v40, v66
	v_mul_f32_e32 v46, v46, v67
	v_cvt_pk_bf16_f32 v142, v40, v46
	v_mov_b32_e32 v50, v192
	v_mov_b32_e32 v51, v193
	v_mul_f32_e32 v40, v68, v41
	v_mul_f32_e32 v41, v68, v123
	v_mul_f32_e32 v46, v68, v102
	v_mul_f32_e32 v40, v40, v50
	v_mul_f32_e32 v41, v41, v51
	v_cvt_pk_bf16_f32 v143, v40, v41
	v_mov_b32_e32 v40, v194
	v_mov_b32_e32 v41, v195
	v_mul_f32_e32 v50, v68, v104
	v_mul_f32_e32 v40, v46, v40
	v_mul_f32_e32 v41, v50, v41
	v_cvt_pk_bf16_f32 v144, v40, v41
	v_mov_b32_e32 v40, v208
	v_mov_b32_e32 v41, v209
	v_mul_f32_e32 v46, v68, v103
	v_mul_f32_e32 v50, v68, v105
	v_mul_f32_e32 v40, v46, v40
	v_mul_f32_e32 v41, v50, v41
	v_cvt_pk_bf16_f32 v145, v40, v41
	v_mov_b32_e32 v40, v210
	v_mov_b32_e32 v41, v211
	v_mul_f32_e32 v46, v68, v106
	v_mul_f32_e32 v50, v68, v54
	v_lshlrev_b32_e32 v54, 16, v9
	v_mul_f32_e32 v40, v46, v40
	v_mul_f32_e32 v41, v50, v41
	v_cvt_pk_bf16_f32 v146, v40, v41
	v_mov_b32_e32 v40, v240
	v_mov_b32_e32 v41, v241
	v_mul_f32_e32 v46, v68, v107
	v_mul_f32_e32 v50, v68, v55
	v_lshlrev_b32_e32 v55, 16, v5
	v_mov_b32_e32 v110, v55
	v_mul_f32_e32 v40, v46, v40
	v_mul_f32_e32 v41, v50, v41
	v_cvt_pk_bf16_f32 v147, v40, v41
	v_mov_b32_e32 v40, v242
	v_mov_b32_e32 v41, v243
	v_mul_f32_e32 v46, v68, v112
	v_mul_f32_e32 v50, v68, v62
	v_mul_f32_e32 v40, v46, v40
	v_mul_f32_e32 v41, v50, v41
	v_cvt_pk_bf16_f32 v148, v40, v41
	global_load_dwordx2 v[40:41], v[36:37], off offset:328
	global_load_dwordx2 v[164:165], v[36:37], off offset:336
	global_load_dwordx2 v[166:167], v[36:37], off offset:344
	global_load_dwordx2 v[168:169], v[36:37], off offset:384
	global_load_dwordx2 v[170:171], v[36:37], off offset:392
	global_load_dwordx2 v[172:173], v[36:37], off offset:400
	global_load_dwordx2 v[174:175], v[36:37], off offset:408
	global_load_dwordx2 v[176:177], v[36:37], off offset:448
	global_load_dwordx2 v[178:179], v[36:37], off offset:456
	global_load_dwordx2 v[180:181], v[36:37], off offset:464
	global_load_dwordx2 v[182:183], v[36:37], off offset:472
	v_mul_f32_e32 v46, v68, v113
	v_mul_f32_e32 v50, v68, v63
	v_mov_b32_e32 v113, v85
	s_waitcnt vmcnt(0) lgkmcnt(0)
	v_mul_f32_e32 v40, v46, v40
	v_mul_f32_e32 v41, v50, v41
	v_cvt_pk_bf16_f32 v149, v40, v41
	v_mov_b32_e32 v40, v164
	v_mov_b32_e32 v41, v165
	v_mul_f32_e32 v46, v68, v114
	v_mul_f32_e32 v50, v68, v64
	v_mov_b32_e32 v114, v86
	v_mul_f32_e32 v40, v46, v40
	v_mul_f32_e32 v41, v50, v41
	v_cvt_pk_bf16_f32 v150, v40, v41
	v_mov_b32_e32 v40, v166
	v_mov_b32_e32 v41, v167
	v_mul_f32_e32 v46, v68, v115
	v_mul_f32_e32 v50, v68, v65
	v_mov_b32_e32 v115, v88
	v_mul_f32_e32 v40, v46, v40
	v_mul_f32_e32 v41, v50, v41
	v_cvt_pk_bf16_f32 v151, v40, v41
	v_mov_b32_e32 v40, v168
	v_mov_b32_e32 v41, v169
	v_mul_f32_e32 v46, v68, v120
	v_mul_f32_e32 v50, v68, v121
	v_mov_b32_e32 v120, v93
	v_mov_b32_e32 v121, v89
	v_pk_mul_f32 v[120:121], v[120:121], v[120:121]
	v_mul_f32_e32 v40, v46, v40
	v_mul_f32_e32 v41, v50, v41
	v_cvt_pk_bf16_f32 v152, v40, v41
	v_mov_b32_e32 v40, v170
	v_mov_b32_e32 v41, v171
	v_mul_f32_e32 v46, v68, v52
	v_mul_f32_e32 v50, v68, v53
	v_and_b32_e32 v53, 0xffff0000, v5
	v_and_b32_e32 v52, 0xffff0000, v9
	v_mov_b32_e32 v112, v53
	v_pk_mul_f32 v[112:113], v[112:113], v[112:113]
	v_mov_b32_e32 v126, v52
	v_mul_f32_e32 v40, v46, v40
	v_mul_f32_e32 v41, v50, v41
	v_cvt_pk_bf16_f32 v153, v40, v41
	v_mov_b32_e32 v40, v172
	v_mov_b32_e32 v41, v173
	v_mul_f32_e32 v46, v68, v48
	v_lshlrev_b64 v[50:51], 5, v[196:197]
	v_mul_f32_e32 v40, v46, v40
	v_mul_f32_e32 v41, v44, v41
	v_cvt_pk_bf16_f32 v154, v40, v41
	v_mov_b32_e32 v40, v174
	v_mov_b32_e32 v41, v175
	v_lshlrev_b32_e32 v46, 3, v58
	v_or_b32_e32 v50, v50, v46
	v_lshlrev_b32_e32 v44, 16, v32
	v_and_b32_e32 v32, 0xffff0000, v32
	v_mov_b32_e32 v163, v32
	v_mov_b32_e32 v161, v44
	v_mul_f32_e32 v40, v42, v40
	v_mul_f32_e32 v38, v38, v41
	v_cvt_pk_bf16_f32 v155, v40, v38
	v_mov_b32_e32 v40, v176
	v_mov_b32_e32 v41, v177
	v_mul_f32_e32 v38, v68, v49
	v_mul_f32_e32 v42, v68, v45
	v_lshl_add_u64 v[48:49], s[0:1], 0, v[0:1]
	v_mul_f32_e32 v0, v68, v47
	v_lshlrev_b32_e32 v45, 16, v10
	v_mov_b32_e32 v106, v45
	v_mul_f32_e32 v38, v38, v40
	v_mul_f32_e32 v40, v42, v41
	v_cvt_pk_bf16_f32 v156, v38, v40
	v_mov_b32_e32 v40, v178
	v_mov_b32_e32 v41, v179
	v_mul_f32_e32 v38, v68, v124
	v_mul_f32_e32 v42, v68, v125
	v_mov_b32_e32 v124, v54
	v_mul_f32_e32 v38, v38, v40
	v_mul_f32_e32 v40, v42, v41
	v_cvt_pk_bf16_f32 v157, v38, v40
	v_mov_b32_e32 v40, v180
	v_mov_b32_e32 v41, v181
	v_mul_f32_e32 v38, v68, v43
	v_and_b32_e32 v43, 0xffff0000, v11
	v_and_b32_e32 v42, 0xffff0000, v33
	v_mov_b32_e32 v109, v43
	v_pk_mul_f32 v[104:105], v[42:43], v[42:43]
	v_mul_f32_e32 v38, v38, v40
	v_mul_f32_e32 v39, v39, v41
	v_cvt_pk_bf16_f32 v158, v38, v39
	v_mov_b32_e32 v62, v182
	v_mov_b32_e32 v63, v183
	v_lshlrev_b64 v[36:37], 2, v[50:51]
	v_lshl_add_u64 v[74:75], s[46:47], 0, v[36:37]
	v_lshl_add_u64 v[78:79], s[48:49], 0, v[36:37]
	v_or_b32_e32 v36, 16, v36
	v_lshl_add_u64 v[76:77], s[46:47], 0, v[36:37]
	v_lshl_add_u64 v[80:81], s[48:49], 0, v[36:37]
	v_and_b32_e32 v37, 0xffff0000, v13
	v_and_b32_e32 v36, 0xffff0000, v35
	v_lshlrev_b32_e32 v39, 16, v12
	v_and_b32_e32 v35, 0xffff0000, v12
	v_lshlrev_b32_e32 v41, 16, v11
	v_lshlrev_b32_e32 v40, 16, v33
	v_and_b32_e32 v33, 0xffff0000, v10
	v_mov_b32_e32 v100, v37
	v_mov_b32_e32 v101, v35
	v_mov_b32_e32 v108, v33
	v_mov_b32_e32 v99, v39
	v_mov_b32_e32 v107, v41
	v_pk_mul_f32 v[100:101], v[100:101], v[100:101]
	v_pk_mul_f32 v[108:109], v[108:109], v[108:109]
	v_lshlrev_b32_e32 v38, 16, v34
	v_and_b32_e32 v34, 0xffff0000, v34
	v_pk_mul_f32 v[102:103], v[40:41], v[40:41]
	v_pk_fma_f32 v[98:99], v[98:99], v[98:99], v[100:101]
	v_pk_fma_f32 v[100:101], v[106:107], v[106:107], v[108:109]
	v_pk_fma_f32 v[108:109], v[118:119], v[118:119], v[120:121]
	v_mov_b32_e32 v127, v34
	v_pk_fma_f32 v[106:107], v[110:111], v[110:111], v[112:113]
	v_mov_b32_e32 v117, v102
	v_pk_add_f32 v[100:101], v[100:101], v[100:101] op_sel:[0,1] op_sel_hi:[1,0]
	v_pk_add_f32 v[102:103], v[108:109], v[108:109] op_sel:[0,1] op_sel_hi:[1,0]
	v_pk_mul_f32 v[122:123], v[126:127], v[126:127]
	v_pk_mul_f32 v[126:127], v[162:163], v[162:163]
	v_pk_add_f32 v[100:101], v[98:99], v[100:101] op_sel:[1,0] op_sel_hi:[0,1]
	v_pk_add_f32 v[102:103], v[106:107], v[102:103] op_sel:[1,0] op_sel_hi:[0,1]
	v_pk_mul_f32 v[96:97], v[36:37], v[36:37]
	v_mov_b32_e32 v125, v38
	v_pk_fma_f32 v[112:113], v[160:161], v[160:161], v[126:127]
	v_pk_add_f32 v[98:99], v[98:99], v[100:101]
	v_pk_add_f32 v[100:101], v[106:107], v[102:103]
	v_pk_fma_f32 v[110:111], v[124:125], v[124:125], v[122:123]
	v_mov_b32_e32 v101, v94
	v_mov_b32_e32 v99, v96
	v_pk_add_f32 v[94:95], v[100:101], v[98:99]
	v_or_b32_e32 v50, 16, v50
	v_mul_f32_e32 v2, v2, v63
	v_mul_f32_e32 v0, v0, v62
	v_cvt_pk_bf16_f32 v159, v0, v2
	global_load_dwordx4 v[62:65], v[48:49], off offset:128
	global_load_dwordx4 v[66:69], v[48:49], off offset:144
	global_load_dwordx4 v[70:73], v[48:49], off
	global_load_dwordx4 v[10:13], v[48:49], off offset:16
	global_load_dwordx4 v[6:9], v[76:77], off
	global_load_dwordx4 v[2:5], v[80:81], off
	s_nop 0
	global_load_dwordx4 v[74:77], v[74:75], off
	s_nop 0
	global_load_dwordx4 v[78:81], v[78:79], off
	v_mul_f32_e32 v0, v88, v88
	v_pk_fma_f32 v[114:115], v[114:115], v[114:115], v[0:1] op_sel_hi:[1,1,0]
	s_waitcnt vmcnt(0) lgkmcnt(0)
	v_mov_b32_e32 v106, v64
	v_mov_b32_e32 v115, v104
	v_pk_add_f32 v[104:105], v[116:117], v[114:115]
	v_mov_b32_e32 v98, v68
	v_pk_add_f32 v[104:105], v[112:113], v[104:105]
	v_mov_b32_e32 v99, v12
	v_pk_add_f32 v[102:103], v[110:111], v[104:105]
	v_mov_b32_e32 v107, v72
	v_pk_add_f32 v[94:95], v[94:95], v[102:103]
	v_mov_b32_e32 v102, v66
	v_pk_add_f32 v[94:95], v[94:95], v[94:95] op_sel:[0,1] op_sel_hi:[1,0]
	v_mov_b32_e32 v103, v10
	v_mov_b32_e32 v0, v94
	s_nop 1
	v_permlane32_swap_b32_e32 v94, v0
	v_add_f32_e32 v0, v94, v0
	v_fmamk_f32 v0, v0, 0x3c800000, v207
	v_mul_f32_e32 v47, 0x4b800000, v0
	v_cmp_gt_f32_e32 vcc, s87, v0
	v_mov_b32_e32 v110, v62
	v_mov_b32_e32 v111, v70
	v_cndmask_b32_e32 v0, v0, v47, vcc
	v_rsq_f32_e32 v0, v0
	v_mov_b32_e32 v70, v63
	v_mov_b32_e32 v72, v65
	v_mov_b32_e32 v10, v67
	v_mul_f32_e32 v47, 0x45800000, v0
	v_cndmask_b32_e32 v0, v0, v47, vcc
	v_pk_mul_f32 v[90:91], v[0:1], v[90:91] op_sel_hi:[0,1]
	v_pk_mul_f32 v[92:93], v[0:1], v[92:93] op_sel_hi:[0,1]
	v_pk_mul_f32 v[86:87], v[0:1], v[86:87] op_sel_hi:[0,1]
	v_pk_mul_f32 v[88:89], v[0:1], v[88:89] op_sel_hi:[0,1]
	v_pk_mul_f32 v[82:83], v[0:1], v[82:83] op_sel_hi:[0,1]
	v_pk_mul_f32 v[84:85], v[0:1], v[84:85] op_sel_hi:[0,1]
	v_pk_mul_f32 v[54:55], v[0:1], v[54:55] op_sel_hi:[0,1]
	v_pk_mul_f32 v[52:53], v[0:1], v[52:53] op_sel_hi:[0,1]
	v_mov_b32_e32 v12, v69
	v_mov_b32_e32 v100, v8
	v_mov_b32_e32 v101, v4
	v_mov_b32_e32 v104, v6
	v_mov_b32_e32 v105, v2
	v_mov_b32_e32 v108, v76
	v_mov_b32_e32 v109, v80
	v_mov_b32_e32 v112, v74
	v_mov_b32_e32 v113, v78
	v_mov_b32_e32 v114, v78
	v_mov_b32_e32 v115, v74
	v_mov_b32_e32 v74, v79
	v_mov_b32_e32 v78, v75
	v_mov_b32_e32 v62, v80
	v_mov_b32_e32 v63, v76
	v_mov_b32_e32 v76, v81
	v_mov_b32_e32 v80, v77
	v_mov_b32_e32 v64, v2
	v_mov_b32_e32 v65, v6
	v_mov_b32_e32 v6, v3
	v_mov_b32_e32 v2, v7
	v_mov_b32_e32 v66, v4
	v_mov_b32_e32 v67, v8
	v_mov_b32_e32 v8, v5
	v_pk_mul_f32 v[68:69], v[90:91], v[110:111]
	v_pk_mul_f32 v[70:71], v[92:93], v[70:71]
	v_pk_mul_f32 v[86:87], v[86:87], v[106:107]
	v_pk_mul_f32 v[72:73], v[88:89], v[72:73]
	v_pk_mul_f32 v[82:83], v[82:83], v[102:103]
	v_pk_mul_f32 v[10:11], v[84:85], v[10:11]
	v_pk_mul_f32 v[54:55], v[54:55], v[98:99]
	v_pk_mul_f32 v[12:13], v[52:53], v[12:13]
	v_mov_b32_e32 v4, v9
	v_pk_mul_f32 v[52:53], v[68:69], v[114:115]
	v_pk_mul_f32 v[68:69], v[68:69], v[112:113]
	v_pk_mul_f32 v[74:75], v[70:71], v[74:75]
	v_pk_mul_f32 v[70:71], v[70:71], v[78:79]
	v_pk_mul_f32 v[62:63], v[86:87], v[62:63]
	v_pk_mul_f32 v[78:79], v[86:87], v[108:109]
	v_pk_mul_f32 v[76:77], v[72:73], v[76:77]
	v_pk_mul_f32 v[72:73], v[72:73], v[80:81]
	v_pk_mul_f32 v[64:65], v[82:83], v[64:65]
	v_pk_mul_f32 v[6:7], v[10:11], v[6:7]
	v_pk_mul_f32 v[2:3], v[10:11], v[2:3]
	v_pk_mul_f32 v[10:11], v[54:55], v[66:67]
	v_pk_mul_f32 v[54:55], v[54:55], v[100:101]
	v_pk_mul_f32 v[8:9], v[12:13], v[8:9]
	v_lshlrev_b64 v[94:95], 2, v[50:51]
	v_pk_mul_f32 v[80:81], v[82:83], v[104:105]
	v_pk_mul_f32 v[4:5], v[12:13], v[4:5]
	v_sub_f32_e32 v12, v53, v52
	v_add_f32_e32 v13, v68, v69
	v_sub_f32_e32 v47, v75, v74
	v_add_f32_e32 v52, v70, v71
	v_sub_f32_e32 v53, v63, v62
	v_add_f32_e32 v61, v78, v79
	v_add_f32_e32 v63, v72, v73
	v_sub_f32_e32 v64, v65, v64
	v_sub_f32_e32 v6, v7, v6
	v_add_f32_e32 v7, v54, v55
	v_sub_f32_e32 v8, v9, v8
	v_lshl_add_u64 v[50:51], s[48:49], 0, v[94:95]
	v_sub_f32_e32 v62, v77, v76
	v_add_f32_e32 v65, v80, v81
	v_add_f32_e32 v2, v2, v3
	v_sub_f32_e32 v3, v11, v10
	v_add_f32_e32 v4, v4, v5
	v_mul_f32_e32 v5, 0x3dd53b94, v12
	v_mul_f32_e32 v9, 0x3dd53b94, v13
	v_mul_f32_e32 v10, 0x3dd53b94, v47
	v_mul_f32_e32 v11, 0x3dd53b94, v52
	v_mul_f32_e32 v12, 0x3dd53b94, v53
	v_mul_f32_e32 v13, 0x3dd53b94, v61
	v_mul_f32_e32 v52, 0x3dd53b94, v63
	v_mul_f32_e32 v53, 0x3dd53b94, v64
	v_mul_f32_e32 v6, 0x3dd53b94, v6
	v_mul_f32_e32 v7, 0x3dd53b94, v7
	v_mul_f32_e32 v8, 0x3dd53b94, v8
	v_lshl_add_u64 v[96:97], s[46:47], 0, v[94:95]
	v_mul_f32_e32 v47, 0x3dd53b94, v62
	v_mul_f32_e32 v54, 0x3dd53b94, v65
	v_mul_f32_e32 v2, 0x3dd53b94, v2
	v_mul_f32_e32 v3, 0x3dd53b94, v3
	v_mul_f32_e32 v4, 0x3dd53b94, v4
	v_cvt_pk_bf16_f32 v160, v5, v10
	v_cvt_pk_bf16_f32 v161, v12, v47
	v_cvt_pk_bf16_f32 v162, v53, v6
	v_cvt_pk_bf16_f32 v163, v3, v8
	v_cvt_pk_bf16_f32 v164, v9, v11
	v_cvt_pk_bf16_f32 v165, v13, v52
	v_cvt_pk_bf16_f32 v166, v54, v2
	v_cvt_pk_bf16_f32 v167, v7, v4
	global_load_dwordx4 v[6:9], v[48:49], off offset:192
	global_load_dwordx4 v[10:13], v[48:49], off offset:64
	s_nop 0
	global_load_dwordx4 v[50:53], v[50:51], off
	s_nop 0
	global_load_dwordx4 v[62:65], v[96:97], off
	v_or_b32_e32 v94, 16, v94
	v_lshl_add_u64 v[2:3], s[46:47], 0, v[94:95]
	v_lshl_add_u64 v[4:5], s[48:49], 0, v[94:95]
	global_load_dwordx4 v[66:69], v[48:49], off offset:208
	global_load_dwordx4 v[70:73], v[48:49], off offset:80
	global_load_dwordx4 v[74:77], v[4:5], off
	global_load_dwordx4 v[78:81], v[2:3], off
	v_mul_hi_i32 v2, v56, s81
	v_lshrrev_b32_e32 v3, 31, v2
	v_ashrrev_i32_e32 v2, 2, v2
	v_pk_mul_f32 v[44:45], v[0:1], v[44:45] op_sel_hi:[0,1]
	v_add_u32_e32 v3, v2, v3
	v_pk_mul_f32 v[32:33], v[0:1], v[32:33] op_sel_hi:[0,1]
	v_pk_mul_f32 v[40:41], v[0:1], v[40:41] op_sel_hi:[0,1]
	v_pk_mul_f32 v[42:43], v[0:1], v[42:43] op_sel_hi:[0,1]
	v_pk_mul_f32 v[38:39], v[0:1], v[38:39] op_sel_hi:[0,1]
	v_pk_mul_f32 v[34:35], v[0:1], v[34:35] op_sel_hi:[0,1]
	v_pk_mul_f32 v[14:15], v[0:1], v[14:15] op_sel_hi:[0,1]
	v_pk_mul_f32 v[36:37], v[0:1], v[36:37] op_sel_hi:[0,1]
	v_mul_lo_u32 v2, v3, 24
	v_sub_u32_e32 v2, v56, v2
	v_lshlrev_b32_e32 v5, 3, v2
	v_cmp_lt_i32_e32 vcc, 15, v2
	s_waitcnt vmcnt(0) lgkmcnt(0)
	v_mov_b32_e32 v48, v6
	v_mov_b32_e32 v49, v10
	v_mov_b32_e32 v54, v50
	v_mov_b32_e32 v55, v62
	v_mov_b32_e32 v10, v7
	v_mov_b32_e32 v6, v8
	v_mov_b32_e32 v7, v12
	v_mov_b32_e32 v12, v9
	v_mov_b32_e32 v8, v66
	v_mov_b32_e32 v9, v70
	v_mov_b32_e32 v70, v67
	v_mov_b32_e32 v66, v68
	v_mov_b32_e32 v67, v72
	v_mov_b32_e32 v72, v69
	v_pk_mul_f32 v[44:45], v[44:45], v[48:49]
	v_mov_b32_e32 v82, v62
	v_mov_b32_e32 v83, v50
	v_mov_b32_e32 v62, v51
	v_mov_b32_e32 v50, v63
	v_mov_b32_e32 v84, v52
	v_mov_b32_e32 v85, v64
	v_mov_b32_e32 v86, v64
	v_mov_b32_e32 v87, v52
	v_mov_b32_e32 v64, v53
	v_mov_b32_e32 v52, v65
	v_mov_b32_e32 v88, v74
	v_mov_b32_e32 v89, v78
	v_mov_b32_e32 v90, v78
	v_mov_b32_e32 v91, v74
	v_mov_b32_e32 v78, v75
	v_mov_b32_e32 v74, v79
	v_mov_b32_e32 v92, v76
	v_mov_b32_e32 v93, v80
	v_mov_b32_e32 v94, v80
	v_mov_b32_e32 v95, v76
	v_mov_b32_e32 v80, v77
	v_mov_b32_e32 v76, v81
	v_pk_mul_f32 v[10:11], v[32:33], v[10:11]
	v_pk_mul_f32 v[6:7], v[40:41], v[6:7]
	v_pk_mul_f32 v[12:13], v[42:43], v[12:13]
	v_pk_mul_f32 v[8:9], v[38:39], v[8:9]
	v_pk_mul_f32 v[32:33], v[34:35], v[70:71]
	v_pk_mul_f32 v[14:15], v[14:15], v[66:67]
	v_pk_mul_f32 v[34:35], v[36:37], v[72:73]
	v_pk_mul_f32 v[36:37], v[44:45], v[54:55]
	v_pk_mul_f32 v[38:39], v[44:45], v[82:83]
	v_pk_mul_f32 v[40:41], v[10:11], v[62:63]
	v_pk_mul_f32 v[10:11], v[10:11], v[50:51]
	v_pk_mul_f32 v[42:43], v[6:7], v[84:85]
	v_pk_mul_f32 v[6:7], v[6:7], v[86:87]
	v_pk_mul_f32 v[44:45], v[12:13], v[64:65]
	v_pk_mul_f32 v[12:13], v[12:13], v[52:53]
	v_pk_mul_f32 v[48:49], v[8:9], v[88:89]
	v_pk_mul_f32 v[8:9], v[8:9], v[90:91]
	v_pk_mul_f32 v[50:51], v[32:33], v[78:79]
	v_pk_mul_f32 v[32:33], v[32:33], v[74:75]
	v_pk_mul_f32 v[52:53], v[14:15], v[92:93]
	v_pk_mul_f32 v[14:15], v[14:15], v[94:95]
	v_pk_mul_f32 v[54:55], v[34:35], v[80:81]
	v_pk_mul_f32 v[34:35], v[34:35], v[76:77]
	v_sub_f32_e32 v0, v37, v36
	v_add_f32_e32 v4, v38, v39
	v_sub_f32_e32 v36, v41, v40
	v_add_f32_e32 v10, v10, v11
	v_sub_f32_e32 v11, v43, v42
	v_add_f32_e32 v6, v6, v7
	v_sub_f32_e32 v7, v45, v44
	v_add_f32_e32 v12, v12, v13
	v_sub_f32_e32 v13, v49, v48
	v_add_f32_e32 v8, v8, v9
	v_sub_f32_e32 v9, v51, v50
	v_add_f32_e32 v32, v32, v33
	v_sub_f32_e32 v33, v53, v52
	v_add_f32_e32 v14, v14, v15
	v_sub_f32_e32 v15, v55, v54
	v_add_f32_e32 v34, v34, v35
	v_mul_f32_e32 v0, 0x3dd53b94, v0
	v_mul_f32_e32 v4, 0x3dd53b94, v4
	v_mul_f32_e32 v35, 0x3dd53b94, v36
	v_mul_f32_e32 v10, 0x3dd53b94, v10
	v_mul_f32_e32 v11, 0x3dd53b94, v11
	v_mul_f32_e32 v6, 0x3dd53b94, v6
	v_mul_f32_e32 v7, 0x3dd53b94, v7
	v_mul_f32_e32 v12, 0x3dd53b94, v12
	v_mul_f32_e32 v13, 0x3dd53b94, v13
	v_mul_f32_e32 v8, 0x3dd53b94, v8
	v_mul_f32_e32 v9, 0x3dd53b94, v9
	v_mul_f32_e32 v32, 0x3dd53b94, v32
	v_mul_f32_e32 v33, 0x3dd53b94, v33
	v_mul_f32_e32 v14, 0x3dd53b94, v14
	v_mul_f32_e32 v15, 0x3dd53b94, v15
	v_mul_f32_e32 v34, 0x3dd53b94, v34
	v_cvt_pk_bf16_f32 v168, v0, v35
	v_cvt_pk_bf16_f32 v169, v11, v7
	v_cvt_pk_bf16_f32 v170, v13, v9
	v_cvt_pk_bf16_f32 v171, v33, v15
	v_cvt_pk_bf16_f32 v172, v4, v10
	v_cvt_pk_bf16_f32 v173, v6, v12
	v_cvt_pk_bf16_f32 v174, v8, v32
	v_cvt_pk_bf16_f32 v175, v14, v34
	s_and_saveexec_b64 s[0:1], vcc
	s_xor_b64 s[0:1], exec, s[0:1]
	v_lshl_add_u32 v0, v3, 6, v5
	v_sub_u32_e32 v0, 0x7f, v0
	s_andn2_saveexec_b64 s[0:1], s[0:1]
	v_lshl_or_b32 v0, v3, 11, s82
	v_add_u32_e32 v0, v0, v5
	s_or_b64 exec, exec, s[0:1]
	v_add_u32_e32 v2, 0x200, v56
	v_mul_hi_i32 v4, v2, s81
	v_lshrrev_b32_e32 v6, 31, v4
	v_ashrrev_i32_e32 v4, 2, v4
	v_add_u32_e32 v6, v4, v6
	v_mul_lo_u32 v4, v6, 24
	v_sub_u32_e32 v2, v2, v4
	v_lshlrev_b32_e32 v7, 3, v2
	v_cmp_lt_i32_e32 vcc, 15, v2
	s_and_saveexec_b64 s[0:1], vcc
	s_xor_b64 s[0:1], exec, s[0:1]
	v_lshl_add_u32 v2, v6, 6, v7
	v_sub_u32_e32 v2, 0x7f, v2
	s_andn2_saveexec_b64 s[0:1], s[0:1]
	v_lshl_or_b32 v2, v6, 11, s82
	v_add_u32_e32 v2, v2, v7
	s_or_b64 exec, exec, s[0:1]
	v_add_u32_e32 v4, 0x400, v56
	v_mul_hi_i32 v8, v4, s81
	v_lshrrev_b32_e32 v9, 31, v8
	v_ashrrev_i32_e32 v8, 2, v8
	v_add_u32_e32 v8, v8, v9
	v_mul_lo_u32 v9, v8, 24
	v_sub_u32_e32 v4, v4, v9
	v_lshlrev_b32_e32 v9, 3, v4
	v_cmp_lt_i32_e32 vcc, 15, v4
	s_and_saveexec_b64 s[0:1], vcc
	s_xor_b64 s[0:1], exec, s[0:1]
	v_lshl_add_u32 v4, v8, 6, v9
	v_sub_u32_e32 v4, 0x7f, v4
	s_andn2_saveexec_b64 s[0:1], s[0:1]
	v_lshl_or_b32 v4, v8, 11, s82
	v_add_u32_e32 v4, v4, v9
	s_or_b64 exec, exec, s[0:1]
	v_mul_lo_u32 v6, v6, s84
	v_add_lshl_u32 v224, v6, v7, 1
	v_not_b32_e32 v6, v0
	v_mov_b32_e32 v7, v1
	v_lshlrev_b64 v[14:15], 1, v[0:1]
	v_lshlrev_b64 v[44:45], 1, v[6:7]
	v_lshl_add_u64 v[10:11], s[4:5], 0, v[14:15]
	v_lshl_add_u64 v[12:13], s[66:67], 0, v[44:45]
	v_cmp_gt_i32_e32 vcc, 0, v0
	v_mul_lo_u32 v3, v3, s84
	v_add_lshl_u32 v225, v3, v5, 1
	v_cndmask_b32_e32 v11, v11, v13, vcc
	v_cndmask_b32_e32 v10, v10, v12, vcc
	global_load_dwordx4 v[32:35], v[10:11], off
	v_mov_b32_e32 v3, v1
	v_not_b32_e32 v10, v2
	v_mov_b32_e32 v11, v1
	v_lshlrev_b64 v[62:63], 1, v[2:3]
	v_lshlrev_b64 v[64:65], 1, v[10:11]
	v_lshl_add_u64 v[12:13], s[4:5], 0, v[62:63]
	v_lshl_add_u64 v[36:37], s[66:67], 0, v[64:65]
	v_cmp_gt_i32_e64 s[36:37], 0, v2
	v_mov_b32_e32 v5, v1
	v_mul_lo_u32 v8, v8, s84
	v_cndmask_b32_e64 v13, v13, v37, s[36:37]
	v_cndmask_b32_e64 v12, v12, v36, s[36:37]
	global_load_dwordx4 v[36:39], v[12:13], off
	v_not_b32_e32 v12, v4
	v_mov_b32_e32 v13, v1
	v_lshlrev_b64 v[66:67], 1, v[4:5]
	v_lshlrev_b64 v[68:69], 1, v[12:13]
	v_add_lshl_u32 v199, v8, v9, 1
	v_ashrrev_i32_e32 v8, 3, v56
	v_lshl_add_u64 v[40:41], s[4:5], 0, v[66:67]
	v_lshl_add_u64 v[42:43], s[66:67], 0, v[68:69]
	v_cmp_gt_i32_e64 s[38:39], 0, v4
	v_add_u32_e32 v48, s82, v8
	v_lshlrev_b32_e32 v9, 4, v56
	v_cndmask_b32_e64 v41, v41, v43, s[38:39]
	v_cndmask_b32_e64 v40, v40, v42, s[38:39]
	global_load_dwordx4 v[40:43], v[40:41], off
	v_and_b32_e32 v70, 0x70, v9
	v_mov_b32_e32 v71, v1
	v_ashrrev_i32_e32 v49, 31, v48
	v_lshl_add_u64 v[52:53], s[56:57], 0, v[70:71]
	v_lshlrev_b64 v[72:73], 15, v[48:49]
	v_lshl_add_u64 v[48:49], v[52:53], 0, v[72:73]
	v_lshl_add_u64 v[74:75], v[72:73], 0, s[22:23]
	global_load_dwordx4 v[48:51], v[48:49], off
	v_lshl_add_u64 v[52:53], v[52:53], 0, v[74:75]
	global_load_dwordx4 v[52:55], v[52:53], off
	v_add_u32_e32 v9, 0, v225
	s_movk_i32 s0, 0x90
	v_lshl_add_u64 v[14:15], s[30:31], 0, v[14:15]
	s_waitcnt vmcnt(0) lgkmcnt(0)
	ds_write_b128 v9, v[32:35]
	v_add_u32_e32 v9, 0, v224
	v_lshl_add_u64 v[32:33], s[50:51], 0, v[44:45]
	v_cndmask_b32_e32 v15, v15, v33, vcc
	v_cndmask_b32_e32 v14, v14, v32, vcc
	v_lshl_add_u64 v[32:33], s[50:51], 0, v[64:65]
	ds_write_b128 v9, v[36:39]
	v_add_u32_e32 v9, 0, v199
	ds_write_b128 v9, v[40:43]
	v_mul_lo_u32 v9, v8, s0
	v_and_b32_e32 v233, 0x60, v70
	v_add_u32_e32 v9, v9, v233
	v_and_b32_e32 v233, 16, v70
	v_lshrrev_b32_e32 v233, 1, v233
	v_add_u32_e32 v233, v233, v9
	v_add_u32_e32 v9, 0xc800, v233
	v_cmp_lt_i32_e64 s[0:1], 3, v60
	ds_write2_b64 v9, v[48:49], v[50:51] offset1:2
	v_add_u32_e32 v9, 0xec00, v233
	ds_write2_b64 v9, v[52:53], v[54:55] offset1:2
	global_load_dwordx4 v[176:179], v[14:15], off
	v_lshl_add_u64 v[14:15], s[30:31], 0, v[62:63]
	v_cndmask_b32_e64 v15, v15, v33, s[36:37]
	v_cndmask_b32_e64 v14, v14, v32, s[36:37]
	global_load_dwordx4 v[180:183], v[14:15], off
	v_lshl_add_u64 v[14:15], s[30:31], 0, v[66:67]
	v_lshl_add_u64 v[32:33], s[50:51], 0, v[68:69]
	v_cndmask_b32_e64 v15, v15, v33, s[38:39]
	v_cndmask_b32_e64 v14, v14, v32, s[38:39]
	global_load_dwordx4 v[184:187], v[14:15], off
	v_lshl_add_u64 v[14:15], s[44:45], 0, v[70:71]
	v_lshl_add_u64 v[32:33], v[14:15], 0, v[72:73]
	v_lshl_add_u64 v[14:15], v[14:15], 0, v[74:75]
	v_lshl_add_u64 v[32:33], v[32:33], 0, s[74:75]
	v_lshl_add_u64 v[14:15], v[14:15], 0, s[74:75]
	global_load_dwordx4 v[188:191], v[32:33], off
	global_load_dwordx4 v[192:195], v[14:15], off
	s_and_saveexec_b64 s[78:79], s[0:1]
	s_setprio 1
	s_or_b64 exec, exec, s[78:79]
	s_movk_i32 s0, 0x190
	v_mad_u32_u24 v9, v57, s0, 0
	v_mul_i32_i24_e32 v14, 0xffffff00, v57
	v_lshl_add_u32 v236, v58, 4, v9
	v_add3_u32 v237, v9, v14, v46
	v_add_u32_e32 v237, v237, v46
	v_ashrrev_i32_e32 v9, 31, v8
	v_lshlrev_b64 v[14:15], 15, v[8:9]
	v_and_b32_e32 v9, 7, v56
	v_add_u32_e32 v8, s69, v8
	v_lshlrev_b32_e32 v32, 4, v9
	v_ashrrev_i32_e32 v9, 31, v8
	v_lshl_add_u64 v[14:15], s[62:63], 0, v[14:15]
	v_mov_b32_e32 v33, v1
	v_lshlrev_b64 v[8:9], 15, v[8:9]
	v_lshl_add_u64 v[200:201], v[14:15], 0, v[32:33]
	v_lshl_add_u64 v[8:9], s[60:61], 0, v[8:9]
	v_mov_b32_e32 v14, v1
	v_mov_b32_e32 v15, v1
	s_lshl_b32 s92, s6, 2
	v_or_b32_e32 v235, 31, v59
	v_lshlrev_b32_e32 v234, 2, v58
	v_lshl_add_u64 v[202:203], v[8:9], 0, v[32:33]
	v_lshl_add_u64 v[204:205], v[4:5], 1, s[70:71]
	v_lshl_add_u64 v[214:215], v[2:3], 1, s[70:71]
	v_lshl_add_u64 v[216:217], v[0:1], 1, s[70:71]
	v_lshl_add_u64 v[218:219], v[12:13], 1, s[72:73]
	v_lshl_add_u64 v[220:221], v[10:11], 1, s[72:73]
	v_lshl_add_u64 v[222:223], v[6:7], 1, s[72:73]
	v_mov_b32_e32 v0, v1
	v_mov_b32_e32 v2, v1
	v_mov_b32_e32 v3, v1
	v_mov_b32_e32 v4, v1
	v_mov_b32_e32 v5, v1
	v_mov_b32_e32 v6, v1
	v_mov_b32_e32 v7, v1
	v_mov_b32_e32 v8, v1
	v_mov_b32_e32 v9, v1
	v_mov_b32_e32 v10, v1
	v_mov_b32_e32 v11, v1
	v_mov_b32_e32 v12, v1
	v_mov_b32_e32 v13, v1
	v_mov_b64_e32 v[46:47], v[14:15]
	v_mov_b64_e32 v[62:63], v[14:15]
	v_mov_b64_e32 v[78:79], v[14:15]
	v_mov_b64_e32 v[94:95], v[14:15]
	s_xor_b64 s[78:79], s[76:77], -1
	s_mov_b32 s7, 2
	s_add_i32 s6, s92, 4
	s_addk_i32 s68, 0x100
	s_mov_b32 s85, 0
	v_mov_b32_e32 v238, 0
	v_mov_b64_e32 v[44:45], v[12:13]
	v_mov_b64_e32 v[42:43], v[10:11]
	v_mov_b64_e32 v[40:41], v[8:9]
	v_mov_b64_e32 v[38:39], v[6:7]
	v_mov_b64_e32 v[36:37], v[4:5]
	v_mov_b64_e32 v[34:35], v[2:3]
	v_mov_b64_e32 v[32:33], v[0:1]
	v_mov_b64_e32 v[60:61], v[12:13]
	v_mov_b64_e32 v[58:59], v[10:11]
	v_mov_b64_e32 v[56:57], v[8:9]
	v_mov_b64_e32 v[54:55], v[6:7]
	v_mov_b64_e32 v[52:53], v[4:5]
	v_mov_b64_e32 v[50:51], v[2:3]
	v_mov_b64_e32 v[48:49], v[0:1]
	v_mov_b64_e32 v[76:77], v[12:13]
	v_mov_b64_e32 v[74:75], v[10:11]
	v_mov_b64_e32 v[72:73], v[8:9]
	v_mov_b64_e32 v[70:71], v[6:7]
	v_mov_b64_e32 v[68:69], v[4:5]
	v_mov_b64_e32 v[66:67], v[2:3]
	v_mov_b64_e32 v[64:65], v[0:1]
	v_mov_b64_e32 v[92:93], v[12:13]
	v_mov_b64_e32 v[90:91], v[10:11]
	v_mov_b64_e32 v[88:89], v[8:9]
	v_mov_b64_e32 v[86:87], v[6:7]
	v_mov_b64_e32 v[84:85], v[4:5]
	v_mov_b64_e32 v[82:83], v[2:3]
	v_mov_b64_e32 v[80:81], v[0:1]
	v_lshl_add_u64 v[2:3], s[8:9], 0, v[216:217]
	v_lshl_add_u64 v[4:5], s[8:9], 0, v[222:223]
	v_cndmask_b32_e32 v217, v3, v5, vcc
	v_cndmask_b32_e32 v216, v2, v4, vcc
	v_lshl_add_u64 v[2:3], s[8:9], 0, v[214:215]
	v_lshl_add_u64 v[4:5], s[8:9], 0, v[220:221]
	v_cndmask_b32_e64 v215, v3, v5, s[36:37]
	v_cndmask_b32_e64 v214, v2, v4, s[36:37]
	v_lshl_add_u64 v[2:3], s[8:9], 0, v[204:205]
	v_lshl_add_u64 v[4:5], s[8:9], 0, v[218:219]
	v_cndmask_b32_e64 v205, v3, v5, s[38:39]
	v_cndmask_b32_e64 v204, v2, v4, s[38:39]
	v_mov_b32_e32 v2, s24
	v_mov_b32_e32 v3, s25
	v_mov_b32_e32 v4, s26
	v_mov_b32_e32 v5, s27
	v_cndmask_b32_e32 v222, v2, v4, vcc
	v_cndmask_b32_e32 v223, v3, v5, vcc
	v_cndmask_b32_e64 v220, v2, v4, s[36:37]
	v_cndmask_b32_e64 v221, v3, v5, s[36:37]
	v_cndmask_b32_e64 v218, v2, v4, s[38:39]
	v_cndmask_b32_e64 v219, v3, v5, s[38:39]
	v_lshl_add_u64 v[200:201], s[8:9], 0, v[200:201]
	v_lshl_add_u64 v[202:203], s[8:9], 0, v[202:203]
	s_branch .LBB0_398
.LBB0_396:
	s_nop 8
	v_exp_f32_e32 v0, v112
	v_exp_f32_e32 v2, v113
	v_exp_f32_e32 v3, v114
	v_exp_f32_e32 v4, v115
	v_add_f32_e32 v5, 0, v0
	v_exp_f32_e32 v6, v116
	v_add_f32_e32 v5, v2, v5
	v_exp_f32_e32 v7, v117
	v_add_f32_e32 v5, v3, v5
	v_exp_f32_e32 v8, v118
	v_add_f32_e32 v5, v4, v5
	v_exp_f32_e32 v9, v119
	v_add_f32_e32 v5, v6, v5
	v_exp_f32_e32 v10, v120
	v_add_f32_e32 v5, v7, v5
	v_exp_f32_e32 v11, v121
	v_add_f32_e32 v5, v8, v5
	v_exp_f32_e32 v12, v122
	v_add_f32_e32 v5, v9, v5
	v_exp_f32_e32 v13, v123
	v_add_f32_e32 v5, v10, v5
	v_exp_f32_e32 v14, v124
	v_add_f32_e32 v5, v11, v5
	v_exp_f32_e32 v15, v125
	v_add_f32_e32 v5, v12, v5
	v_exp_f32_e32 v112, v126
	v_add_f32_e32 v5, v13, v5
	v_exp_f32_e32 v113, v127
	v_add_f32_e32 v5, v14, v5
	v_exp_f32_e32 v96, v96
	v_add_f32_e32 v5, v15, v5
	v_exp_f32_e32 v97, v97
	v_add_f32_e32 v5, v112, v5
	v_exp_f32_e32 v98, v98
	v_add_f32_e32 v5, v113, v5
	v_exp_f32_e32 v99, v99
	v_add_f32_e32 v5, v96, v5
	v_exp_f32_e32 v100, v100
	v_add_f32_e32 v5, v97, v5
	v_exp_f32_e32 v101, v101
	v_add_f32_e32 v5, v98, v5
	v_exp_f32_e32 v102, v102
	v_add_f32_e32 v5, v99, v5
	v_exp_f32_e32 v103, v103
	v_add_f32_e32 v5, v100, v5
	v_exp_f32_e32 v104, v104
	v_add_f32_e32 v5, v101, v5
	v_exp_f32_e32 v105, v105
	v_add_f32_e32 v5, v102, v5
	v_exp_f32_e32 v106, v106
	v_add_f32_e32 v5, v103, v5
	v_exp_f32_e32 v107, v107
	v_add_f32_e32 v5, v104, v5
	v_exp_f32_e32 v108, v108
	v_add_f32_e32 v5, v105, v5
	v_exp_f32_e32 v109, v109
	v_add_f32_e32 v5, v106, v5
	v_exp_f32_e32 v110, v110
	v_add_f32_e32 v5, v107, v5
	v_exp_f32_e32 v111, v111
	v_add_f32_e32 v5, v108, v5
	v_add_f32_e32 v5, v109, v5
	s_mulk_i32 s28, 0x4800
	v_add_f32_e32 v5, v110, v5
	v_add_f32_e32 v124, v111, v5
	v_cvt_pk_bf16_f32 v2, v0, v2
	v_cvt_pk_bf16_f32 v3, v3, v4
	v_cvt_pk_bf16_f32 v4, v6, v7
	v_cvt_pk_bf16_f32 v5, v8, v9
	v_cvt_pk_bf16_f32 v6, v10, v11
	v_cvt_pk_bf16_f32 v7, v12, v13
	v_cvt_pk_bf16_f32 v8, v14, v15
	v_cvt_pk_bf16_f32 v9, v112, v113
	v_cvt_pk_bf16_f32 v10, v96, v97
	v_cvt_pk_bf16_f32 v11, v98, v99
	v_cvt_pk_bf16_f32 v12, v100, v101
	v_cvt_pk_bf16_f32 v13, v102, v103
	v_cvt_pk_bf16_f32 v96, v104, v105
	v_cvt_pk_bf16_f32 v97, v106, v107
	v_cvt_pk_bf16_f32 v98, v108, v109
	v_cvt_pk_bf16_f32 v99, v110, v111
	v_add_u32_e32 v0, s28, v237
	v_add_u32_e32 v14, 0xc800, v0
	v_add_u32_e32 v15, 0xda00, v0
	v_add_u32_e32 v125, 0xec00, v0
	v_add_u32_e32 v0, 0xfe00, v0
	ds_read_b128 v[100:103], v14
	ds_read_b128 v[104:107], v15
	ds_read_b128 v[108:111], v125
	ds_read_b128 v[112:115], v0
	ds_read_b128 v[116:119], v14 offset:32
	ds_read_b128 v[120:123], v15 offset:32
	s_waitcnt lgkmcnt(4)
	v_mfma_f32_32x32x16_bf16 v[80:95], v[100:103], v[2:5], v[80:95]
	v_mfma_f32_32x32x16_bf16 v[64:79], v[104:107], v[2:5], v[64:79]
	ds_read_b128 v[100:103], v125 offset:32
	ds_read_b128 v[104:107], v0 offset:32
	s_waitcnt lgkmcnt(4)
	v_mfma_f32_32x32x16_bf16 v[48:63], v[108:111], v[2:5], v[48:63]
	v_mfma_f32_32x32x16_bf16 v[32:47], v[112:115], v[2:5], v[32:47]
	ds_read_b128 v[2:5], v14 offset:64
	ds_read_b128 v[108:111], v15 offset:64
	s_waitcnt lgkmcnt(4)
	v_mfma_f32_32x32x16_bf16 v[80:95], v[116:119], v[6:9], v[80:95]
	v_mfma_f32_32x32x16_bf16 v[64:79], v[120:123], v[6:9], v[64:79]
	ds_read_b128 v[112:115], v125 offset:64
	ds_read_b128 v[116:119], v0 offset:64
	s_waitcnt lgkmcnt(4)
	v_mfma_f32_32x32x16_bf16 v[48:63], v[100:103], v[6:9], v[48:63]
	v_mfma_f32_32x32x16_bf16 v[32:47], v[104:107], v[6:9], v[32:47]
	ds_read_b128 v[6:9], v14 offset:96
	ds_read_b128 v[100:103], v15 offset:96
	s_waitcnt lgkmcnt(4)
	v_mfma_f32_32x32x16_bf16 v[80:95], v[2:5], v[10:13], v[80:95]
	v_mfma_f32_32x32x16_bf16 v[64:79], v[108:111], v[10:13], v[64:79]
	ds_read_b128 v[2:5], v125 offset:96
	ds_read_b128 v[104:107], v0 offset:96
	s_waitcnt lgkmcnt(4)
	v_mfma_f32_32x32x16_bf16 v[48:63], v[112:115], v[10:13], v[48:63]
	v_mfma_f32_32x32x16_bf16 v[32:47], v[116:119], v[10:13], v[32:47]
	s_waitcnt lgkmcnt(2)
	v_mfma_f32_32x32x16_bf16 v[80:95], v[6:9], v[96:99], v[80:95]
	v_mfma_f32_32x32x16_bf16 v[64:79], v[100:103], v[96:99], v[64:79]
	s_waitcnt lgkmcnt(0)
	v_mfma_f32_32x32x16_bf16 v[48:63], v[2:5], v[96:99], v[48:63]
	v_mfma_f32_32x32x16_bf16 v[32:47], v[104:107], v[96:99], v[32:47]
	v_add_f32_e32 v238, v238, v124

.LBB0_398:
	s_add_i32 s29, s7, -2
	s_and_b32 s28, s29, 1
	s_add_i32 s0, s7, -1
	s_cmp_ge_u32 s0, s6
	s_waitcnt lgkmcnt(0)
	s_barrier
	s_mul_i32 s1, s28, 0x6400
	v_add_u32_e32 v0, s1, v236
	ds_read_b128 v[2:5], v0
	ds_read_b128 v[6:9], v0 offset:32
	ds_read_b128 v[10:13], v0 offset:12800
	ds_read_b128 v[208:211], v0 offset:12832
	ds_read_b128 v[240:243], v0 offset:64
	ds_read_b128 v[244:247], v0 offset:12864
	s_cbranch_scc1 .LBB0_401
	s_xor_b32 s0, s28, 1
	s_mul_i32 s1, s0, 0x6400
	s_add_i32 s1, s1, 0
	v_add_u32_e32 v15, s1, v225
	s_waitcnt vmcnt(0)
	ds_write_b128 v15, v[176:179]
	v_add_u32_e32 v15, s1, v224
	ds_write_b128 v15, v[180:183]
	v_add_u32_e32 v15, s1, v199
	s_mulk_i32 s0, 0x4800
	ds_write_b128 v15, v[184:187]
	v_add_u32_e32 v15, s0, v233
	v_add_u32_e32 v14, 0xc800, v15
	v_add_u32_e32 v15, 0xec00, v15
	s_cmp_ge_u32 s7, s6
	ds_write2_b64 v14, v[188:189], v[190:191] offset1:2
	ds_write2_b64 v15, v[192:193], v[194:195] offset1:2
	s_cbranch_scc1 .LBB0_401
	global_load_dwordx4 v[176:179], v[216:217], off
	global_load_dwordx4 v[180:183], v[214:215], off
	global_load_dwordx4 v[184:187], v[204:205], off
	global_load_dwordx4 v[188:191], v[200:201], off
	global_load_dwordx4 v[192:195], v[202:203], off
